# same relaxation for the SSD in-projection copy: explicit vmcnt(4) at K-loop exit, then the peeled iteration's first wait does not drain the epilogue stores
# baseline (speedup 1.0000x reference)
.LBB0_132:
	s_ashr_i32 s25, s24, 31
	s_lshl_b64 s[28:29], s[24:25], 20
	v_readlane_b32 s25, v254, 62
	s_add_u32 s28, s25, s28
	v_readlane_b32 s25, v254, 63
	s_addc_u32 s29, s25, s29
	s_and_b64 s[4:5], s[4:5], exec
	s_cselect_b32 s25, s29, s31
	s_cselect_b32 s37, s28, s30
	s_add_u32 s50, s30, 0x100
	s_addc_u32 s51, s31, 0
	s_mov_b32 s57, -2
	s_add_u32 vcc_lo, s0, 0xffffc000
	s_addc_u32 vcc_hi, s1, -1
	s_mov_b32 m0, s52
	s_nop 0
	global_load_lds_dwordx4 v158, vcc
	s_mov_b32 m0, s53
	s_nop 0
	global_load_lds_dwordx4 v160, vcc
	ds_read_b128 v[130:133], v224
	ds_read_b128 v[134:137], v224 offset:1024
	ds_read_b128 v[138:141], v224 offset:2048
	ds_read_b128 v[142:145], v224 offset:3072
	ds_read_b128 v[146:149], v224 offset:16384
	ds_read_b128 v[162:165], v224 offset:17408
	ds_read_b128 v[166:169], v224 offset:18432
	ds_read_b128 v[170:173], v224 offset:19456
	ds_read_b128 v[174:177], v225
	ds_read_b128 v[178:181], v225 offset:1024
	ds_read_b128 v[182:185], v225 offset:2048
	ds_read_b128 v[186:189], v225 offset:3072
	ds_read_b128 v[190:193], v225 offset:4096
	ds_read_b128 v[204:207], v225 offset:5120
	ds_read_b128 v[208:211], v225 offset:6144
	ds_read_b128 v[212:215], v225 offset:7168
	s_add_u32 s4, s0, 0x100
	s_addc_u32 s5, s1, 0
	s_add_i32 s58, 0, 0x10000
	s_cmp_eq_u32 s57, 28
	s_cselect_b32 s35, s27, s5
	s_cselect_b32 s34, s26, s4
	s_cselect_b32 s31, s25, s51
	s_cselect_b32 s30, s37, s50
	s_add_i32 s59, 0, 0x14000
	s_add_i32 m0, s38, 0xc000
	s_nop 0
	global_load_lds_dwordx4 v158, s[0:1]
	s_add_i32 m0, s38, 0xe000
	s_nop 0
	global_load_lds_dwordx4 v160, s[0:1]
	s_waitcnt vmcnt(48)
	s_waitcnt lgkmcnt(0)
	v_mfma_f32_16x16x32_bf16 v[126:129], v[130:133], v[174:177], 0
	v_mfma_f32_16x16x32_bf16 v[126:129], v[134:137], v[178:181], v[126:129]
	s_barrier
	s_setprio 1
	v_mfma_f32_16x16x32_bf16 v[122:125], v[142:145], v[178:181], 0
	v_mfma_f32_16x16x32_bf16 v[122:125], v[138:141], v[174:177], v[122:125]
	v_mfma_f32_16x16x32_bf16 v[106:109], v[138:141], v[182:185], 0
	v_mfma_f32_16x16x32_bf16 v[106:109], v[142:145], v[186:189], v[106:109]
	v_mfma_f32_16x16x32_bf16 v[110:113], v[134:137], v[186:189], 0
	v_mfma_f32_16x16x32_bf16 v[110:113], v[130:133], v[182:185], v[110:113]
	v_mfma_f32_16x16x32_bf16 v[94:97], v[130:133], v[190:193], 0
	v_mfma_f32_16x16x32_bf16 v[94:97], v[134:137], v[204:207], v[94:97]
	v_mfma_f32_16x16x32_bf16 v[90:93], v[142:145], v[204:207], 0
	v_mfma_f32_16x16x32_bf16 v[90:93], v[138:141], v[190:193], v[90:93]
	v_mfma_f32_16x16x32_bf16 v[74:77], v[138:141], v[208:211], 0
	v_mfma_f32_16x16x32_bf16 v[74:77], v[142:145], v[212:215], v[74:77]
	v_mfma_f32_16x16x32_bf16 v[78:81], v[134:137], v[212:215], 0
	v_mfma_f32_16x16x32_bf16 v[78:81], v[130:133], v[208:211], v[78:81]
	v_mfma_f32_16x16x32_bf16 v[118:121], v[146:149], v[174:177], 0
	v_mfma_f32_16x16x32_bf16 v[118:121], v[162:165], v[178:181], v[118:121]
	v_mfma_f32_16x16x32_bf16 v[114:117], v[170:173], v[178:181], 0
	v_mfma_f32_16x16x32_bf16 v[114:117], v[166:169], v[174:177], v[114:117]
	v_mfma_f32_16x16x32_bf16 v[98:101], v[166:169], v[182:185], 0
	v_mfma_f32_16x16x32_bf16 v[98:101], v[170:173], v[186:189], v[98:101]
	v_mfma_f32_16x16x32_bf16 v[102:105], v[162:165], v[186:189], 0
	v_mfma_f32_16x16x32_bf16 v[102:105], v[146:149], v[182:185], v[102:105]
	v_mfma_f32_16x16x32_bf16 v[86:89], v[146:149], v[190:193], 0
	v_mfma_f32_16x16x32_bf16 v[86:89], v[162:165], v[204:207], v[86:89]
	v_mfma_f32_16x16x32_bf16 v[82:85], v[170:173], v[204:207], 0
	v_mfma_f32_16x16x32_bf16 v[82:85], v[166:169], v[190:193], v[82:85]
	v_mfma_f32_16x16x32_bf16 v[66:69], v[166:169], v[208:211], 0
	v_mfma_f32_16x16x32_bf16 v[66:69], v[170:173], v[212:215], v[66:69]
	v_mfma_f32_16x16x32_bf16 v[70:73], v[162:165], v[212:215], 0
	v_mfma_f32_16x16x32_bf16 v[70:73], v[146:149], v[208:211], v[70:73]
	s_setprio 0
	s_barrier
	ds_read_b128 v[174:177], v225 offset:16384
	ds_read_b128 v[178:181], v225 offset:17408
	ds_read_b128 v[182:185], v225 offset:18432
	ds_read_b128 v[186:189], v225 offset:19456
	ds_read_b128 v[190:193], v225 offset:20480
	ds_read_b128 v[204:207], v225 offset:21504
	ds_read_b128 v[208:211], v225 offset:22528
	ds_read_b128 v[212:215], v225 offset:23552
	s_add_i32 s0, s58, s15
	s_mov_b32 m0, s0
	s_nop 0
	global_load_lds_dwordx4 v152, s[30:31]
	s_add_i32 m0, s0, 0x2000
	s_add_u32 s0, s30, 0x80000
	s_addc_u32 s1, s31, 0
	s_add_i32 s58, s59, s15
	global_load_lds_dwordx4 v156, s[30:31]
	s_mov_b32 m0, s58
	s_nop 0
	global_load_lds_dwordx4 v152, s[0:1]
	s_add_i32 m0, s58, 0x2000
	s_nop 0
	global_load_lds_dwordx4 v156, s[0:1]
	s_waitcnt vmcnt(6)
	s_waitcnt lgkmcnt(0)
	v_mfma_f32_16x16x32_bf16 v[62:65], v[130:133], v[174:177], 0
	v_mfma_f32_16x16x32_bf16 v[62:65], v[134:137], v[178:181], v[62:65]
	s_barrier
	s_setprio 1
	v_mfma_f32_16x16x32_bf16 v[58:61], v[142:145], v[178:181], 0
	v_mfma_f32_16x16x32_bf16 v[58:61], v[138:141], v[174:177], v[58:61]
	v_mfma_f32_16x16x32_bf16 v[42:45], v[138:141], v[182:185], 0
	v_mfma_f32_16x16x32_bf16 v[42:45], v[142:145], v[186:189], v[42:45]
	v_mfma_f32_16x16x32_bf16 v[46:49], v[134:137], v[186:189], 0
	v_mfma_f32_16x16x32_bf16 v[46:49], v[130:133], v[182:185], v[46:49]
	v_mfma_f32_16x16x32_bf16 v[30:33], v[130:133], v[190:193], 0
	v_mfma_f32_16x16x32_bf16 v[30:33], v[134:137], v[204:207], v[30:33]
	v_mfma_f32_16x16x32_bf16 v[26:29], v[142:145], v[204:207], 0
	v_mfma_f32_16x16x32_bf16 v[26:29], v[138:141], v[190:193], v[26:29]
	v_mfma_f32_16x16x32_bf16 v[10:13], v[138:141], v[208:211], 0
	v_mfma_f32_16x16x32_bf16 v[10:13], v[142:145], v[212:215], v[10:13]
	v_mfma_f32_16x16x32_bf16 v[14:17], v[134:137], v[212:215], 0
	v_mfma_f32_16x16x32_bf16 v[14:17], v[130:133], v[208:211], v[14:17]
	v_mfma_f32_16x16x32_bf16 v[54:57], v[146:149], v[174:177], 0
	v_mfma_f32_16x16x32_bf16 v[54:57], v[162:165], v[178:181], v[54:57]
	v_mfma_f32_16x16x32_bf16 v[50:53], v[170:173], v[178:181], 0
	v_mfma_f32_16x16x32_bf16 v[50:53], v[166:169], v[174:177], v[50:53]
	v_mfma_f32_16x16x32_bf16 v[34:37], v[166:169], v[182:185], 0
	v_mfma_f32_16x16x32_bf16 v[34:37], v[170:173], v[186:189], v[34:37]
	v_mfma_f32_16x16x32_bf16 v[38:41], v[162:165], v[186:189], 0
	v_mfma_f32_16x16x32_bf16 v[38:41], v[146:149], v[182:185], v[38:41]
	v_mfma_f32_16x16x32_bf16 v[22:25], v[146:149], v[190:193], 0
	v_mfma_f32_16x16x32_bf16 v[22:25], v[162:165], v[204:207], v[22:25]
	v_mfma_f32_16x16x32_bf16 v[18:21], v[170:173], v[204:207], 0
	v_mfma_f32_16x16x32_bf16 v[18:21], v[166:169], v[190:193], v[18:21]
	v_mfma_f32_16x16x32_bf16 v[2:5], v[166:169], v[208:211], 0
	v_mfma_f32_16x16x32_bf16 v[2:5], v[170:173], v[212:215], v[2:5]
	v_mfma_f32_16x16x32_bf16 v[6:9], v[162:165], v[212:215], 0
	v_mfma_f32_16x16x32_bf16 v[6:9], v[146:149], v[208:211], v[6:9]
	s_setprio 0
	s_barrier
	s_mov_b32 m0, s38
	s_nop 0
	global_load_lds_dwordx4 v150, s[34:35]
	s_mov_b32 m0, s39
	s_nop 0
	global_load_lds_dwordx4 v154, s[34:35]
	ds_read_b128 v[130:133], v224 offset:32768
	ds_read_b128 v[134:137], v224 offset:33792
	ds_read_b128 v[138:141], v224 offset:34816
	ds_read_b128 v[142:145], v224 offset:35840
	ds_read_b128 v[146:149], v224 offset:49152
	ds_read_b128 v[162:165], v224 offset:50176
	ds_read_b128 v[166:169], v224 offset:51200
	ds_read_b128 v[170:173], v224 offset:52224
	ds_read_b128 v[174:177], v225 offset:32768
	ds_read_b128 v[178:181], v225 offset:33792
	ds_read_b128 v[182:185], v225 offset:34816
	ds_read_b128 v[186:189], v225 offset:35840
	ds_read_b128 v[190:193], v225 offset:36864
	ds_read_b128 v[204:207], v225 offset:37888
	ds_read_b128 v[208:211], v225 offset:38912
	ds_read_b128 v[212:215], v225 offset:39936
	s_add_i32 s58, 0, 0x18000
	s_add_i32 s59, 0, 0x1c000
	s_add_u32 s0, s34, 0x4000
	s_addc_u32 s1, s35, 0
	s_mov_b32 m0, s40
	s_nop 0
	global_load_lds_dwordx4 v150, s[0:1]
	s_mov_b32 m0, s41
	s_nop 0
	global_load_lds_dwordx4 v154, s[0:1]
	s_waitcnt vmcnt(8)
	s_waitcnt lgkmcnt(0)
	v_mfma_f32_16x16x32_bf16 v[126:129], v[130:133], v[174:177], v[126:129]
	v_mfma_f32_16x16x32_bf16 v[126:129], v[134:137], v[178:181], v[126:129]
	s_barrier
	s_setprio 1
	v_mfma_f32_16x16x32_bf16 v[122:125], v[142:145], v[178:181], v[122:125]
	v_mfma_f32_16x16x32_bf16 v[122:125], v[138:141], v[174:177], v[122:125]
	v_mfma_f32_16x16x32_bf16 v[106:109], v[138:141], v[182:185], v[106:109]
	v_mfma_f32_16x16x32_bf16 v[106:109], v[142:145], v[186:189], v[106:109]
	v_mfma_f32_16x16x32_bf16 v[110:113], v[134:137], v[186:189], v[110:113]
	v_mfma_f32_16x16x32_bf16 v[110:113], v[130:133], v[182:185], v[110:113]
	v_mfma_f32_16x16x32_bf16 v[94:97], v[130:133], v[190:193], v[94:97]
	v_mfma_f32_16x16x32_bf16 v[94:97], v[134:137], v[204:207], v[94:97]
	v_mfma_f32_16x16x32_bf16 v[90:93], v[142:145], v[204:207], v[90:93]
	v_mfma_f32_16x16x32_bf16 v[90:93], v[138:141], v[190:193], v[90:93]
	v_mfma_f32_16x16x32_bf16 v[74:77], v[138:141], v[208:211], v[74:77]
	v_mfma_f32_16x16x32_bf16 v[74:77], v[142:145], v[212:215], v[74:77]
	v_mfma_f32_16x16x32_bf16 v[78:81], v[134:137], v[212:215], v[78:81]
	v_mfma_f32_16x16x32_bf16 v[78:81], v[130:133], v[208:211], v[78:81]
	v_mfma_f32_16x16x32_bf16 v[118:121], v[146:149], v[174:177], v[118:121]
	v_mfma_f32_16x16x32_bf16 v[118:121], v[162:165], v[178:181], v[118:121]
	v_mfma_f32_16x16x32_bf16 v[114:117], v[170:173], v[178:181], v[114:117]
	v_mfma_f32_16x16x32_bf16 v[114:117], v[166:169], v[174:177], v[114:117]
	v_mfma_f32_16x16x32_bf16 v[98:101], v[166:169], v[182:185], v[98:101]
	v_mfma_f32_16x16x32_bf16 v[98:101], v[170:173], v[186:189], v[98:101]
	v_mfma_f32_16x16x32_bf16 v[102:105], v[162:165], v[186:189], v[102:105]
	v_mfma_f32_16x16x32_bf16 v[102:105], v[146:149], v[182:185], v[102:105]
	v_mfma_f32_16x16x32_bf16 v[86:89], v[146:149], v[190:193], v[86:89]
	v_mfma_f32_16x16x32_bf16 v[86:89], v[162:165], v[204:207], v[86:89]
	v_mfma_f32_16x16x32_bf16 v[82:85], v[170:173], v[204:207], v[82:85]
	v_mfma_f32_16x16x32_bf16 v[82:85], v[166:169], v[190:193], v[82:85]
	v_mfma_f32_16x16x32_bf16 v[66:69], v[166:169], v[208:211], v[66:69]
	v_mfma_f32_16x16x32_bf16 v[66:69], v[170:173], v[212:215], v[66:69]
	v_mfma_f32_16x16x32_bf16 v[70:73], v[162:165], v[212:215], v[70:73]
	v_mfma_f32_16x16x32_bf16 v[70:73], v[146:149], v[208:211], v[70:73]
	s_setprio 0
	s_barrier
	ds_read_b128 v[174:177], v225 offset:49152
	ds_read_b128 v[178:181], v225 offset:50176
	ds_read_b128 v[182:185], v225 offset:51200
	ds_read_b128 v[186:189], v225 offset:52224
	ds_read_b128 v[190:193], v225 offset:53248
	ds_read_b128 v[204:207], v225 offset:54272
	ds_read_b128 v[208:211], v225 offset:55296
	ds_read_b128 v[212:215], v225 offset:56320
	s_add_i32 s0, s58, s15
	s_add_u32 vcc_lo, s30, s94
	s_addc_u32 vcc_hi, s31, s95
	s_mov_b32 m0, s0
	s_nop 0
	global_load_lds_dwordx4 v152, vcc
	s_add_i32 m0, s0, 0x2000
	s_add_u32 s0, s30, 0x80080
	s_addc_u32 s1, s31, 0
	s_add_i32 s30, s59, s15
	global_load_lds_dwordx4 v156, vcc
	s_mov_b32 m0, s30
	s_nop 0
	global_load_lds_dwordx4 v152, s[0:1]
	s_add_i32 m0, s30, 0x2000
	s_nop 0
	global_load_lds_dwordx4 v156, s[0:1]
	s_waitcnt vmcnt(6)
	s_waitcnt lgkmcnt(0)
	v_mfma_f32_16x16x32_bf16 v[62:65], v[130:133], v[174:177], v[62:65]
	v_mfma_f32_16x16x32_bf16 v[62:65], v[134:137], v[178:181], v[62:65]
	s_barrier
	s_setprio 1
	v_mfma_f32_16x16x32_bf16 v[58:61], v[142:145], v[178:181], v[58:61]
	v_mfma_f32_16x16x32_bf16 v[58:61], v[138:141], v[174:177], v[58:61]
	v_mfma_f32_16x16x32_bf16 v[42:45], v[138:141], v[182:185], v[42:45]
	v_mfma_f32_16x16x32_bf16 v[42:45], v[142:145], v[186:189], v[42:45]
	v_mfma_f32_16x16x32_bf16 v[46:49], v[134:137], v[186:189], v[46:49]
	v_mfma_f32_16x16x32_bf16 v[46:49], v[130:133], v[182:185], v[46:49]
	v_mfma_f32_16x16x32_bf16 v[30:33], v[130:133], v[190:193], v[30:33]
	v_mfma_f32_16x16x32_bf16 v[30:33], v[134:137], v[204:207], v[30:33]
	v_mfma_f32_16x16x32_bf16 v[26:29], v[142:145], v[204:207], v[26:29]
	v_mfma_f32_16x16x32_bf16 v[26:29], v[138:141], v[190:193], v[26:29]
	v_mfma_f32_16x16x32_bf16 v[10:13], v[138:141], v[208:211], v[10:13]
	v_mfma_f32_16x16x32_bf16 v[10:13], v[142:145], v[212:215], v[10:13]
	s_add_i32 s57, s57, 2
	v_mfma_f32_16x16x32_bf16 v[14:17], v[134:137], v[212:215], v[14:17]
	v_mfma_f32_16x16x32_bf16 v[14:17], v[130:133], v[208:211], v[14:17]
	s_add_u32 s50, s50, 0x100
	v_mfma_f32_16x16x32_bf16 v[54:57], v[146:149], v[174:177], v[54:57]
	v_mfma_f32_16x16x32_bf16 v[54:57], v[162:165], v[178:181], v[54:57]
	s_addc_u32 s51, s51, 0
	v_mfma_f32_16x16x32_bf16 v[50:53], v[170:173], v[178:181], v[50:53]
	v_mfma_f32_16x16x32_bf16 v[50:53], v[166:169], v[174:177], v[50:53]
	s_cmp_gt_u32 s57, 29
	v_mfma_f32_16x16x32_bf16 v[34:37], v[166:169], v[182:185], v[34:37]
	v_mfma_f32_16x16x32_bf16 v[34:37], v[170:173], v[186:189], v[34:37]
	s_mov_b64 s[0:1], s[4:5]
	v_mfma_f32_16x16x32_bf16 v[38:41], v[162:165], v[186:189], v[38:41]
	v_mfma_f32_16x16x32_bf16 v[38:41], v[146:149], v[182:185], v[38:41]
	v_mfma_f32_16x16x32_bf16 v[22:25], v[146:149], v[190:193], v[22:25]
	v_mfma_f32_16x16x32_bf16 v[22:25], v[162:165], v[204:207], v[22:25]
	v_mfma_f32_16x16x32_bf16 v[18:21], v[170:173], v[204:207], v[18:21]
	v_mfma_f32_16x16x32_bf16 v[18:21], v[166:169], v[190:193], v[18:21]
	v_mfma_f32_16x16x32_bf16 v[2:5], v[166:169], v[208:211], v[2:5]
	v_mfma_f32_16x16x32_bf16 v[2:5], v[170:173], v[212:215], v[2:5]
	v_mfma_f32_16x16x32_bf16 v[6:9], v[162:165], v[212:215], v[6:9]
	v_mfma_f32_16x16x32_bf16 v[6:9], v[146:149], v[208:211], v[6:9]
	s_setprio 0
	s_barrier
	s_cbranch_scc1 .Lpeel_exit_0

.Lpeel_exit_0:
	s_waitcnt vmcnt(4)
